# latent attention: next tile's K/V global loads rotated to the loop bottom (in flight across the tile barrier)
# speedup vs baseline: 1.0079x; 1.0031x over previous
.LBB0_212:
	s_add_i32 s41, s41, 1
	v_add_u32_e32 v178, 0x2000, v178
	s_cmp_eq_u32 s41, 36
	v_add_u32_e32 v167, 0x80, v167
	s_cbranch_scc1 .Lattn_rot_last
	global_load_dwordx4 v[152:155], v167, s[48:49]
	global_load_dwordx4 v[156:159], v167, s[4:5]
	s_cmp_lt_u32 s41, 34
	s_cselect_b64 s[0:1], -1, 0
	s_cmp_gt_u32 s41, 33
	s_cbranch_scc1 .Lattn_rot_nok
	global_load_dwordx4 v[128:131], v178, s[2:3]
	global_load_dwordx4 v[132:135], v178, s[62:63]
.Lattn_rot_nok:
	s_waitcnt lgkmcnt(0)
	s_barrier
	s_mov_b32 s64, s71
	s_branch .LBB0_210
.Lattn_rot_last:
	s_waitcnt lgkmcnt(0)
	s_barrier
